# split-K units store partial sums (no f32 atomics); hand-written res_fix phases 9/12/17 and the final phase add them up deterministically
# baseline (speedup 1.0000x reference)
; __device__ __forceinline__ void res_fix_phase(const Params& p) {
;   u16* xb = (u16*)(p.ws + O_XB);
;   float* part = (float*)(p.ws + O_PART);
;   const int lane = threadIdx.x & 63, wave = threadIdx.x >> 6;
;   for (int row = NP + blockIdx.x * 8 + wave; row < MT; row += gridDim.x * 8) {
;     const float* xr = p.out + (size_t)row * 1024;
;     float ss = 0.f;
; #pragma unroll
;     for (int i = 0; i < 4; i++) {
;       float4 v = *(const float4*)(xr + i * 256 + lane * 4);
;       ss += v.x * v.x + v.y * v.y + v.z * v.z + v.w * v.w;
;       ushort4 o;
;       o.x = f2bf(v.x); o.y = f2bf(v.y); o.z = f2bf(v.z); o.w = f2bf(v.w);
;       *(ushort4*)(xb + (size_t)row * 1024 + i * 256 + lane * 4) = o;
;     }
;     ss = wsum64(ss);
;     if (lane < 16) part[(size_t)row * 16 + lane] = (lane == 0) ? ss : 0.f;
;   }
; }
.LBB0_1239:
	v_lshrrev_b32_e32 v154, 6, v128
	v_and_b32_e32 v153, 63, v128
	v_readlane_b32 s1, v254, 0
	v_readfirstlane_b32 s0, v154
	s_nop 3
	s_lshl_b32 s1, s1, 3
	s_add_u32 s2, s1, s0
	s_cmp_ge_u32 s2, 512
	s_cbranch_scc1 .Lrf_done_9
	v_lshlrev_b32_e32 v150, 4, v153
	v_lshlrev_b32_e32 v151, 3, v153
	v_lshlrev_b32_e32 v152, 2, v153
	v_cmp_eq_u32_e64 s[20:21], 0, v153
	v_cmp_gt_u32_e64 s[22:23], 16, v153
	s_lshl_b32 s3, s2, 12
	s_add_u32 s8, s94, 0x4000000
	s_addc_u32 s9, s95, 0
	s_add_u32 s8, s8, s3
	s_addc_u32 s9, s9, 0
	s_add_u32 s10, s96, 0xd408100
	s_addc_u32 s11, s97, 0
	s_add_u32 s10, s10, s3
	s_addc_u32 s11, s11, 0
	global_load_dwordx4 v[2:5], v150, s[8:9]
	global_load_dwordx4 v[6:9], v150, s[8:9] offset:1024
	global_load_dwordx4 v[10:13], v150, s[8:9] offset:2048
	global_load_dwordx4 v[14:17], v150, s[8:9] offset:3072
	global_load_dwordx4 v[20:23], v150, s[10:11]
	global_load_dwordx4 v[24:27], v150, s[10:11] offset:1024
	global_load_dwordx4 v[28:31], v150, s[10:11] offset:2048
	global_load_dwordx4 v[32:35], v150, s[10:11] offset:3072
	s_add_u32 s10, s10, 0x200000
	s_addc_u32 s11, s11, 0
	global_load_dwordx4 v[36:39], v150, s[10:11]
	global_load_dwordx4 v[40:43], v150, s[10:11] offset:1024
	global_load_dwordx4 v[44:47], v150, s[10:11] offset:2048
	global_load_dwordx4 v[48:51], v150, s[10:11] offset:3072
	s_add_u32 s10, s10, 0x200000
	s_addc_u32 s11, s11, 0
	global_load_dwordx4 v[52:55], v150, s[10:11]
	global_load_dwordx4 v[56:59], v150, s[10:11] offset:1024
	global_load_dwordx4 v[60:63], v150, s[10:11] offset:2048
	global_load_dwordx4 v[64:67], v150, s[10:11] offset:3072
	s_add_u32 s10, s10, 0x200000
	s_addc_u32 s11, s11, 0
	global_load_dwordx4 v[68:71], v150, s[10:11]
	global_load_dwordx4 v[72:75], v150, s[10:11] offset:1024
	global_load_dwordx4 v[76:79], v150, s[10:11] offset:2048
	global_load_dwordx4 v[80:83], v150, s[10:11] offset:3072
	s_waitcnt vmcnt(0)
	v_pk_add_f32 v[2:3], v[2:3], v[20:21]
	v_pk_add_f32 v[4:5], v[4:5], v[22:23]
	v_pk_add_f32 v[6:7], v[6:7], v[24:25]
	v_pk_add_f32 v[8:9], v[8:9], v[26:27]
	v_pk_add_f32 v[10:11], v[10:11], v[28:29]
	v_pk_add_f32 v[12:13], v[12:13], v[30:31]
	v_pk_add_f32 v[14:15], v[14:15], v[32:33]
	v_pk_add_f32 v[16:17], v[16:17], v[34:35]
	v_pk_add_f32 v[2:3], v[2:3], v[36:37]
	v_pk_add_f32 v[4:5], v[4:5], v[38:39]
	v_pk_add_f32 v[6:7], v[6:7], v[40:41]
	v_pk_add_f32 v[8:9], v[8:9], v[42:43]
	v_pk_add_f32 v[10:11], v[10:11], v[44:45]
	v_pk_add_f32 v[12:13], v[12:13], v[46:47]
	v_pk_add_f32 v[14:15], v[14:15], v[48:49]
	v_pk_add_f32 v[16:17], v[16:17], v[50:51]
	v_pk_add_f32 v[2:3], v[2:3], v[52:53]
	v_pk_add_f32 v[4:5], v[4:5], v[54:55]
	v_pk_add_f32 v[6:7], v[6:7], v[56:57]
	v_pk_add_f32 v[8:9], v[8:9], v[58:59]
	v_pk_add_f32 v[10:11], v[10:11], v[60:61]
	v_pk_add_f32 v[12:13], v[12:13], v[62:63]
	v_pk_add_f32 v[14:15], v[14:15], v[64:65]
	v_pk_add_f32 v[16:17], v[16:17], v[66:67]
	v_pk_add_f32 v[2:3], v[2:3], v[68:69]
	v_pk_add_f32 v[4:5], v[4:5], v[70:71]
	v_pk_add_f32 v[6:7], v[6:7], v[72:73]
	v_pk_add_f32 v[8:9], v[8:9], v[74:75]
	v_pk_add_f32 v[10:11], v[10:11], v[76:77]
	v_pk_add_f32 v[12:13], v[12:13], v[78:79]
	v_pk_add_f32 v[14:15], v[14:15], v[80:81]
	v_pk_add_f32 v[16:17], v[16:17], v[82:83]
	global_store_dwordx4 v150, v[2:5], s[8:9]
	global_store_dwordx4 v150, v[6:9], s[8:9] offset:1024
	global_store_dwordx4 v150, v[10:13], s[8:9] offset:2048
	global_store_dwordx4 v150, v[14:17], s[8:9] offset:3072
	v_mul_f32_e32 v154, v2, v2
	v_fmac_f32_e32 v154, v3, v3
	v_fmac_f32_e32 v154, v4, v4
	v_fmac_f32_e32 v154, v5, v5
	v_fmac_f32_e32 v154, v6, v6
	v_fmac_f32_e32 v154, v7, v7
	v_fmac_f32_e32 v154, v8, v8
	v_fmac_f32_e32 v154, v9, v9
	v_fmac_f32_e32 v154, v10, v10
	v_fmac_f32_e32 v154, v11, v11
	v_fmac_f32_e32 v154, v12, v12
	v_fmac_f32_e32 v154, v13, v13
	v_fmac_f32_e32 v154, v14, v14
	v_fmac_f32_e32 v154, v15, v15
	v_fmac_f32_e32 v154, v16, v16
	v_fmac_f32_e32 v154, v17, v17
	s_add_u32 s3, s2, 16384
	s_lshl_b32 s12, s3, 11
	s_add_u32 s14, s96, 0x2f08100
	s_addc_u32 s15, s97, 0
	s_add_u32 s14, s14, s12
	s_addc_u32 s15, s15, 0
	v_cvt_pk_bf16_f32 v156, v2, v3
	v_cvt_pk_bf16_f32 v157, v4, v5
	v_cvt_pk_bf16_f32 v158, v6, v7
	v_cvt_pk_bf16_f32 v159, v8, v9
	v_cvt_pk_bf16_f32 v160, v10, v11
	v_cvt_pk_bf16_f32 v161, v12, v13
	v_cvt_pk_bf16_f32 v162, v14, v15
	v_cvt_pk_bf16_f32 v163, v16, v17
	global_store_dwordx2 v151, v[156:157], s[14:15]
	global_store_dwordx2 v151, v[158:159], s[14:15] offset:512
	global_store_dwordx2 v151, v[160:161], s[14:15] offset:1024
	global_store_dwordx2 v151, v[162:163], s[14:15] offset:1536
	v_add_f32_dpp v154, v154, v154 quad_perm:[1,0,3,2] row_mask:0xf bank_mask:0xf
	s_nop 1
	v_add_f32_dpp v154, v154, v154 quad_perm:[2,3,0,1] row_mask:0xf bank_mask:0xf
	s_nop 1
	v_add_f32_dpp v154, v154, v154 row_half_mirror row_mask:0xf bank_mask:0xf
	s_nop 1
	v_add_f32_dpp v154, v154, v154 row_mirror row_mask:0xf bank_mask:0xf
	v_mov_b32_e32 v155, v154
	s_nop 1
	v_permlane16_swap_b32_e32 v155, v154
	v_add_f32_e32 v154, v154, v155
	v_mov_b32_e32 v155, v154
	s_nop 1
	v_permlane32_swap_b32_e32 v155, v154
	v_add_f32_e32 v154, v154, v155
	v_cndmask_b32_e64 v155, 0, v154, s[20:21]
	s_lshl_b32 s12, s3, 6
	s_add_u32 s14, s96, 0x2e00100
	s_addc_u32 s15, s97, 0
	s_add_u32 s14, s14, s12
	s_addc_u32 s15, s15, 0
	s_mov_b64 s[16:17], exec
	s_mov_b64 exec, s[22:23]
	s_nop 1
	global_store_dword v152, v155, s[14:15]
	s_mov_b64 exec, s[16:17]
; __device__ __forceinline__ void xcd_barrier(const XcdBarrier& b) {
;     asm volatile("s_waitcnt vmcnt(0)" ::: "memory");
;     __syncthreads();
;     if (threadIdx.x == 0) {
;         unsigned* bar = b.bar;
;         __builtin_amdgcn_s_waitcnt(0);
;         unsigned nloc = b.st[0], nx = b.st[1];
;         if (nloc == 0u) { xcd_barrier_complete(bar, b.x, nloc, nx); b.st[0] = nloc; b.st[1] = nx; }
; __device__ __forceinline__ void res_fix_phase(const Params& p) {
;     ...
;   for (int row = NP + blockIdx.x * 8 + wave; row < MT; row += gridDim.x * 8) {
;     const float* xr = p.out + (size_t)row * 1024;
;     float ss = 0.f;
; #pragma unroll
;     for (int i = 0; i < 4; i++) {
;       float4 v = *(const float4*)(xr + i * 256 + lane * 4);
;       ss += v.x * v.x + v.y * v.y + v.z * v.z + v.w * v.w;
;       ushort4 o;
;       o.x = f2bf(v.x); o.y = f2bf(v.y); o.z = f2bf(v.z); o.w = f2bf(v.w);
;       *(ushort4*)(xb + (size_t)row * 1024 + i * 256 + lane * 4) = o;
;     }
;     ss = wsum64(ss);
;     if (lane < 16) part[(size_t)row * 16 + lane] = (lane == 0) ? ss : 0.f;
;   }
.Lrf_done_9:
.LBB0_1245:
	s_cmp_lt_i32 s40, 11
	s_cselect_b64 s[4:5], -1, 0
	s_cmp_gt_i32 s40, 10
	s_cselect_b64 s[0:1], -1, 0
	s_cmp_lt_i32 s41, 10
	s_cselect_b64 s[2:3], -1, 0
	s_or_b64 s[0:1], s[0:1], s[2:3]
	s_and_b64 vcc, exec, s[0:1]
	s_cbranch_vccnz .LBB0_1306
	s_andn2_b64 vcc, exec, s[6:7]
	s_cbranch_vccnz .LBB0_1296
	s_waitcnt vmcnt(0)
	s_waitcnt lgkmcnt(0)
	s_barrier
	s_and_saveexec_b64 s[0:1], s[68:69]
	s_cbranch_execz .LBB0_1295
	v_mov_b32_e32 v0, 0x1c040
	s_waitcnt vmcnt(0) expcnt(0) lgkmcnt(0)
	ds_read_b32 v2, v0
	v_mov_b32_e32 v0, 0x1c044
	ds_read_b32 v0, v0
	s_waitcnt lgkmcnt(1)
	v_cmp_ne_u32_e32 vcc, 0, v2
	s_cbranch_vccnz .LBB0_1263
	v_readlane_b32 s2, v254, 17
	s_mul_i32 s33, s43, s2
	s_add_u32 s2, s96, 0xf928300
	s_addc_u32 s3, s97, 0
	s_add_u32 s6, s96, 0xf928500
	s_addc_u32 s7, s97, 0
	s_add_u32 s8, s96, 0xf928600
	s_addc_u32 s9, s97, 0
	s_add_u32 s10, s96, 0xf928700
	s_addc_u32 s11, s97, 0
	s_add_u32 s12, s96, 0xf928800
	s_addc_u32 s13, s97, 0
	s_add_u32 s14, s96, 0xf928900
	s_addc_u32 s15, s97, 0
	s_add_u32 s16, s96, 0xf928a00
	s_addc_u32 s17, s97, 0
	s_add_u32 s18, s96, 0xf928b00
	s_addc_u32 s19, s97, 0
	s_add_u32 s20, s96, 0xf928c00
	s_addc_u32 s21, s97, 0
	s_add_u32 s22, s96, 0xf928d00
	s_addc_u32 s23, s97, 0
	s_add_u32 s24, s96, 0xf928e00
	s_addc_u32 s25, s97, 0
	s_add_u32 s26, s96, 0xf928f00
	s_addc_u32 s27, s97, 0
	s_add_u32 s28, s96, 0xf929000
	s_addc_u32 s29, s97, 0
	s_add_u32 s30, s96, 0xf929100
	s_addc_u32 s31, s97, 0
	s_add_u32 s34, s96, 0xf929200
	s_addc_u32 s35, s97, 0
	s_add_u32 s36, s96, 0xf929300
	s_addc_u32 s37, s97, 0
	s_add_u32 s38, s96, 0xf929400
	s_mul_i32 s33, s33, s42
	s_addc_u32 s39, s97, 0
	s_mov_b32 s50, 1
	v_mov_b32_e32 v16, 0
	s_branch .LBB0_1251

; template <int EPI>
; __device__ __forceinline__ void gemm_phase(const Params& p, const u16* __restrict__ A, int lda, const u16* __restrict__ BT, int ldb,
;                            int K, int N, u16* __restrict__ outb, int ldo, int resid_in, int boff) {
;     ...
;     if (un >= t_full) { const int v = un - t_full; tl = t_full + v / split; KT = KTALL / split; kbeg = (v % split) * KT; part_unit = true; }
.Lgm_splitk_c:
	s_sub_u32 s36, s5, s28
	s_lshr_b32 s37, s36, s44
	s_lshl_b32 s10, s37, s44
	s_sub_u32 s36, s36, s10
	s_mov_b32 s47, s36
	s_add_u32 s37, s37, s28
	s_lshr_b32 s6, s37, 3
	s_and_b32 s7, s37, 7
	s_lshr_b32 s9, s39, s44
	s_mul_i32 s8, s36, s9
	s_mov_b32 s10, 1

; template <int EPI>
; __device__ __forceinline__ void gemm_phase(const Params& p, const u16* __restrict__ A, int lda, const u16* __restrict__ BT, int ldb,
;                            int K, int N, u16* __restrict__ outb, int ldo, int resid_in, int boff) {
;     ...
;     if (EPI == EPI_RES && part_unit) {
;       float* xfp = p.out;
; #pragma unroll
;       for (int i = 0; i < 16; i++) {
;         const int rl = wm * 64 + 4 * (lane >> 5) + (i & 3) + 8 * (i >> 2);
;         float* r0p = xfp + (size_t)(m0 + rl) * 1024;
;         float* r1p = r0p + (size_t)32 * 1024;
;         atomicAdd(r0p + c0, acc00[i]); atomicAdd(r0p + c1, acc01[i]);
;         atomicAdd(r1p + c0, acc10[i]); atomicAdd(r1p + c1, acc11[i]);
;       }
.Lgc_tailN:
	v_mfma_f32_16x16x32_bf16 v[0:3], v[178:181], v[194:197], v[0:3]
	v_mfma_f32_16x16x32_bf16 v[4:7], v[178:181], v[198:201], v[4:7]
	v_mfma_f32_16x16x32_bf16 v[8:11], v[178:181], v[202:205], v[8:11]
	v_mfma_f32_16x16x32_bf16 v[12:15], v[178:181], v[206:209], v[12:15]
	v_mfma_f32_16x16x32_bf16 v[16:19], v[178:181], v[210:213], v[16:19]
	v_mfma_f32_16x16x32_bf16 v[20:23], v[178:181], v[214:217], v[20:23]
	v_mfma_f32_16x16x32_bf16 v[24:27], v[178:181], v[218:221], v[24:27]
	v_mfma_f32_16x16x32_bf16 v[28:31], v[178:181], v[222:225], v[28:31]
	v_mfma_f32_16x16x32_bf16 v[32:35], v[182:185], v[194:197], v[32:35]
	v_mfma_f32_16x16x32_bf16 v[36:39], v[182:185], v[198:201], v[36:39]
	v_mfma_f32_16x16x32_bf16 v[40:43], v[182:185], v[202:205], v[40:43]
	v_mfma_f32_16x16x32_bf16 v[44:47], v[182:185], v[206:209], v[44:47]
	v_mfma_f32_16x16x32_bf16 v[48:51], v[182:185], v[210:213], v[48:51]
	v_mfma_f32_16x16x32_bf16 v[52:55], v[182:185], v[214:217], v[52:55]
	v_mfma_f32_16x16x32_bf16 v[56:59], v[182:185], v[218:221], v[56:59]
	v_mfma_f32_16x16x32_bf16 v[60:63], v[182:185], v[222:225], v[60:63]
	v_mfma_f32_16x16x32_bf16 v[64:67], v[186:189], v[194:197], v[64:67]
	v_mfma_f32_16x16x32_bf16 v[68:71], v[186:189], v[198:201], v[68:71]
	v_mfma_f32_16x16x32_bf16 v[72:75], v[186:189], v[202:205], v[72:75]
	v_mfma_f32_16x16x32_bf16 v[76:79], v[186:189], v[206:209], v[76:79]
	v_mfma_f32_16x16x32_bf16 v[80:83], v[186:189], v[210:213], v[80:83]
	v_mfma_f32_16x16x32_bf16 v[84:87], v[186:189], v[214:217], v[84:87]
	v_mfma_f32_16x16x32_bf16 v[88:91], v[186:189], v[218:221], v[88:91]
	v_mfma_f32_16x16x32_bf16 v[92:95], v[186:189], v[222:225], v[92:95]
	v_mfma_f32_16x16x32_bf16 v[96:99], v[190:193], v[194:197], v[96:99]
	v_mfma_f32_16x16x32_bf16 v[100:103], v[190:193], v[198:201], v[100:103]
	v_mfma_f32_16x16x32_bf16 v[104:107], v[190:193], v[202:205], v[104:107]
	v_mfma_f32_16x16x32_bf16 v[108:111], v[190:193], v[206:209], v[108:111]
	v_mfma_f32_16x16x32_bf16 v[112:115], v[190:193], v[210:213], v[112:115]
	v_mfma_f32_16x16x32_bf16 v[116:119], v[190:193], v[214:217], v[116:119]
	v_mfma_f32_16x16x32_bf16 v[120:123], v[190:193], v[218:221], v[120:123]
	v_mfma_f32_16x16x32_bf16 v[124:127], v[190:193], v[222:225], v[124:127]
	s_lshl_b32 s11, s6, 8
	s_lshl_b32 s12, s4, 6
	s_add_u32 s11, s11, s12
	v_add_u32_e32 v238, s11, v248
	v_sub_u32_e32 v238, v238, v248
	v_lshl_add_u32 v238, v249, 2, v238
	v_lshlrev_b32_e32 v243, 12, v238
	s_lshl_b32 s11, s7, 7
	v_add_u32_e32 v239, s11, v248
	v_lshlrev_b32_e32 v239, 2, v239
	v_add_u32_e32 v243, v243, v239
	s_nop 7
	s_lshl_b32 s36, s47, 21
	s_add_u32 s36, s36, 0x9408100
	s_add_u32 s36, s96, s36
	s_addc_u32 s37, s97, 0
	global_store_dword v243, v0, s[36:37]
	global_store_dword v243, v4, s[36:37] offset:64
	global_store_dword v243, v8, s[36:37] offset:128
	global_store_dword v243, v12, s[36:37] offset:192
	global_store_dword v243, v16, s[36:37] offset:256
	global_store_dword v243, v20, s[36:37] offset:320
	global_store_dword v243, v24, s[36:37] offset:384
	global_store_dword v243, v28, s[36:37] offset:448
	s_add_u32 s36, s36, 0x1000
	s_addc_u32 s37, s37, 0
	global_store_dword v243, v1, s[36:37]
	global_store_dword v243, v5, s[36:37] offset:64
	global_store_dword v243, v9, s[36:37] offset:128
	global_store_dword v243, v13, s[36:37] offset:192
	global_store_dword v243, v17, s[36:37] offset:256
	global_store_dword v243, v21, s[36:37] offset:320
	global_store_dword v243, v25, s[36:37] offset:384
	global_store_dword v243, v29, s[36:37] offset:448
	s_add_u32 s36, s36, 0x1000
	s_addc_u32 s37, s37, 0
	global_store_dword v243, v2, s[36:37]
	global_store_dword v243, v6, s[36:37] offset:64
	global_store_dword v243, v10, s[36:37] offset:128
	global_store_dword v243, v14, s[36:37] offset:192
	global_store_dword v243, v18, s[36:37] offset:256
	global_store_dword v243, v22, s[36:37] offset:320
	global_store_dword v243, v26, s[36:37] offset:384
	global_store_dword v243, v30, s[36:37] offset:448
	s_add_u32 s36, s36, 0x1000
	s_addc_u32 s37, s37, 0
	global_store_dword v243, v3, s[36:37]
	global_store_dword v243, v7, s[36:37] offset:64
	global_store_dword v243, v11, s[36:37] offset:128
	global_store_dword v243, v15, s[36:37] offset:192
	global_store_dword v243, v19, s[36:37] offset:256
	global_store_dword v243, v23, s[36:37] offset:320
	global_store_dword v243, v27, s[36:37] offset:384
	global_store_dword v243, v31, s[36:37] offset:448
	s_add_u32 s36, s36, 0xd000
	s_addc_u32 s37, s37, 0
	global_store_dword v243, v32, s[36:37]
	global_store_dword v243, v36, s[36:37] offset:64
	global_store_dword v243, v40, s[36:37] offset:128
	global_store_dword v243, v44, s[36:37] offset:192
	global_store_dword v243, v48, s[36:37] offset:256
	global_store_dword v243, v52, s[36:37] offset:320
	global_store_dword v243, v56, s[36:37] offset:384
	global_store_dword v243, v60, s[36:37] offset:448
	s_add_u32 s36, s36, 0x1000
	s_addc_u32 s37, s37, 0
; template <int EPI>
; __device__ __forceinline__ void gemm_phase(const Params& p, const u16* __restrict__ A, int lda, const u16* __restrict__ BT, int ldb,
;                            int K, int N, u16* __restrict__ outb, int ldo, int resid_in, int boff) {
;     ...
;     if (EPI == EPI_RES && part_unit) {
;       float* xfp = p.out;
; #pragma unroll
;       for (int i = 0; i < 16; i++) {
;         const int rl = wm * 64 + 4 * (lane >> 5) + (i & 3) + 8 * (i >> 2);
;         float* r0p = xfp + (size_t)(m0 + rl) * 1024;
;         float* r1p = r0p + (size_t)32 * 1024;
;         atomicAdd(r0p + c0, acc00[i]); atomicAdd(r0p + c1, acc01[i]);
;         atomicAdd(r1p + c0, acc10[i]); atomicAdd(r1p + c1, acc11[i]);
;       }
	global_store_dword v243, v33, s[36:37]
	global_store_dword v243, v37, s[36:37] offset:64
	global_store_dword v243, v41, s[36:37] offset:128
	global_store_dword v243, v45, s[36:37] offset:192
	global_store_dword v243, v49, s[36:37] offset:256
	global_store_dword v243, v53, s[36:37] offset:320
	global_store_dword v243, v57, s[36:37] offset:384
	global_store_dword v243, v61, s[36:37] offset:448
	s_add_u32 s36, s36, 0x1000
	s_addc_u32 s37, s37, 0
	global_store_dword v243, v34, s[36:37]
	global_store_dword v243, v38, s[36:37] offset:64
	global_store_dword v243, v42, s[36:37] offset:128
	global_store_dword v243, v46, s[36:37] offset:192
	global_store_dword v243, v50, s[36:37] offset:256
	global_store_dword v243, v54, s[36:37] offset:320
	global_store_dword v243, v58, s[36:37] offset:384
	global_store_dword v243, v62, s[36:37] offset:448
	s_add_u32 s36, s36, 0x1000
	s_addc_u32 s37, s37, 0
	global_store_dword v243, v35, s[36:37]
	global_store_dword v243, v39, s[36:37] offset:64
	global_store_dword v243, v43, s[36:37] offset:128
	global_store_dword v243, v47, s[36:37] offset:192
	global_store_dword v243, v51, s[36:37] offset:256
	global_store_dword v243, v55, s[36:37] offset:320
	global_store_dword v243, v59, s[36:37] offset:384
	global_store_dword v243, v63, s[36:37] offset:448
	s_add_u32 s36, s36, 0xd000
	s_addc_u32 s37, s37, 0
	global_store_dword v243, v64, s[36:37]
	global_store_dword v243, v68, s[36:37] offset:64
	global_store_dword v243, v72, s[36:37] offset:128
	global_store_dword v243, v76, s[36:37] offset:192
	global_store_dword v243, v80, s[36:37] offset:256
	global_store_dword v243, v84, s[36:37] offset:320
	global_store_dword v243, v88, s[36:37] offset:384
	global_store_dword v243, v92, s[36:37] offset:448
	s_add_u32 s36, s36, 0x1000
	s_addc_u32 s37, s37, 0
	global_store_dword v243, v65, s[36:37]
	global_store_dword v243, v69, s[36:37] offset:64
	global_store_dword v243, v73, s[36:37] offset:128
	global_store_dword v243, v77, s[36:37] offset:192
	global_store_dword v243, v81, s[36:37] offset:256
	global_store_dword v243, v85, s[36:37] offset:320
	global_store_dword v243, v89, s[36:37] offset:384
	global_store_dword v243, v93, s[36:37] offset:448
	s_add_u32 s36, s36, 0x1000
	s_addc_u32 s37, s37, 0
	global_store_dword v243, v66, s[36:37]
	global_store_dword v243, v70, s[36:37] offset:64
	global_store_dword v243, v74, s[36:37] offset:128
	global_store_dword v243, v78, s[36:37] offset:192
	global_store_dword v243, v82, s[36:37] offset:256
	global_store_dword v243, v86, s[36:37] offset:320
	global_store_dword v243, v90, s[36:37] offset:384
	global_store_dword v243, v94, s[36:37] offset:448
	s_add_u32 s36, s36, 0x1000
	s_addc_u32 s37, s37, 0
	global_store_dword v243, v67, s[36:37]
	global_store_dword v243, v71, s[36:37] offset:64
	global_store_dword v243, v75, s[36:37] offset:128
	global_store_dword v243, v79, s[36:37] offset:192
	global_store_dword v243, v83, s[36:37] offset:256
	global_store_dword v243, v87, s[36:37] offset:320
	global_store_dword v243, v91, s[36:37] offset:384
	global_store_dword v243, v95, s[36:37] offset:448
	s_add_u32 s36, s36, 0xd000
	s_addc_u32 s37, s37, 0
	global_store_dword v243, v96, s[36:37]
	global_store_dword v243, v100, s[36:37] offset:64
	global_store_dword v243, v104, s[36:37] offset:128
	global_store_dword v243, v108, s[36:37] offset:192
	global_store_dword v243, v112, s[36:37] offset:256
	global_store_dword v243, v116, s[36:37] offset:320
	global_store_dword v243, v120, s[36:37] offset:384
	global_store_dword v243, v124, s[36:37] offset:448
	s_add_u32 s36, s36, 0x1000
	s_addc_u32 s37, s37, 0
	global_store_dword v243, v97, s[36:37]
	global_store_dword v243, v101, s[36:37] offset:64
	global_store_dword v243, v105, s[36:37] offset:128
	global_store_dword v243, v109, s[36:37] offset:192
	global_store_dword v243, v113, s[36:37] offset:256
	global_store_dword v243, v117, s[36:37] offset:320
	global_store_dword v243, v121, s[36:37] offset:384
	global_store_dword v243, v125, s[36:37] offset:448
	s_add_u32 s36, s36, 0x1000
	s_addc_u32 s37, s37, 0
	global_store_dword v243, v98, s[36:37]
	global_store_dword v243, v102, s[36:37] offset:64
	global_store_dword v243, v106, s[36:37] offset:128
	global_store_dword v243, v110, s[36:37] offset:192
	global_store_dword v243, v114, s[36:37] offset:256
	global_store_dword v243, v118, s[36:37] offset:320
	global_store_dword v243, v122, s[36:37] offset:384
	global_store_dword v243, v126, s[36:37] offset:448
	s_add_u32 s36, s36, 0x1000
	s_addc_u32 s37, s37, 0
	global_store_dword v243, v99, s[36:37]
	global_store_dword v243, v103, s[36:37] offset:64
	global_store_dword v243, v107, s[36:37] offset:128
	global_store_dword v243, v111, s[36:37] offset:192
	global_store_dword v243, v115, s[36:37] offset:256
	global_store_dword v243, v119, s[36:37] offset:320
	global_store_dword v243, v123, s[36:37] offset:384
	global_store_dword v243, v127, s[36:37] offset:448
	s_nop 3
	s_branch .Lgc_next

; __device__ __forceinline__ void res_fix_phase(const Params& p) {
;   u16* xb = (u16*)(p.ws + O_XB);
;   float* part = (float*)(p.ws + O_PART);
;   const int lane = threadIdx.x & 63, wave = threadIdx.x >> 6;
;   for (int row = NP + blockIdx.x * 8 + wave; row < MT; row += gridDim.x * 8) {
;     const float* xr = p.out + (size_t)row * 1024;
;     float ss = 0.f;
; #pragma unroll
;     for (int i = 0; i < 4; i++) {
;       float4 v = *(const float4*)(xr + i * 256 + lane * 4);
;       ss += v.x * v.x + v.y * v.y + v.z * v.z + v.w * v.w;
;       ushort4 o;
;       o.x = f2bf(v.x); o.y = f2bf(v.y); o.z = f2bf(v.z); o.w = f2bf(v.w);
;       *(ushort4*)(xb + (size_t)row * 1024 + i * 256 + lane * 4) = o;
;     }
;     ss = wsum64(ss);
;     if (lane < 16) part[(size_t)row * 16 + lane] = (lane == 0) ? ss : 0.f;
;   }
; }
.LBB0_1509:
	v_lshrrev_b32_e32 v154, 6, v128
	v_and_b32_e32 v153, 63, v128
	v_readlane_b32 s1, v254, 0
	v_readfirstlane_b32 s0, v154
	s_nop 3
	s_lshl_b32 s1, s1, 3
	s_add_u32 s2, s1, s0
	s_cmp_ge_u32 s2, 512
	s_cbranch_scc1 .Lrf_done_12
	v_lshlrev_b32_e32 v150, 4, v153
	v_lshlrev_b32_e32 v151, 3, v153
	v_lshlrev_b32_e32 v152, 2, v153
	v_cmp_eq_u32_e64 s[20:21], 0, v153
	v_cmp_gt_u32_e64 s[22:23], 16, v153
	s_lshl_b32 s3, s2, 12
	s_add_u32 s8, s94, 0x4000000
	s_addc_u32 s9, s95, 0
	s_add_u32 s8, s8, s3
	s_addc_u32 s9, s9, 0
	s_add_u32 s10, s96, 0xd408100
	s_addc_u32 s11, s97, 0
	s_add_u32 s10, s10, s3
	s_addc_u32 s11, s11, 0
	global_load_dwordx4 v[2:5], v150, s[8:9]
	global_load_dwordx4 v[6:9], v150, s[8:9] offset:1024
	global_load_dwordx4 v[10:13], v150, s[8:9] offset:2048
	global_load_dwordx4 v[14:17], v150, s[8:9] offset:3072
	global_load_dwordx4 v[20:23], v150, s[10:11]
	global_load_dwordx4 v[24:27], v150, s[10:11] offset:1024
	global_load_dwordx4 v[28:31], v150, s[10:11] offset:2048
	global_load_dwordx4 v[32:35], v150, s[10:11] offset:3072
	s_add_u32 s10, s10, 0x200000
	s_addc_u32 s11, s11, 0
	global_load_dwordx4 v[36:39], v150, s[10:11]
	global_load_dwordx4 v[40:43], v150, s[10:11] offset:1024
	global_load_dwordx4 v[44:47], v150, s[10:11] offset:2048
	global_load_dwordx4 v[48:51], v150, s[10:11] offset:3072
	s_add_u32 s10, s10, 0x200000
	s_addc_u32 s11, s11, 0
	global_load_dwordx4 v[52:55], v150, s[10:11]
	global_load_dwordx4 v[56:59], v150, s[10:11] offset:1024
	global_load_dwordx4 v[60:63], v150, s[10:11] offset:2048
	global_load_dwordx4 v[64:67], v150, s[10:11] offset:3072
	s_add_u32 s10, s10, 0x200000
	s_addc_u32 s11, s11, 0
	global_load_dwordx4 v[68:71], v150, s[10:11]
	global_load_dwordx4 v[72:75], v150, s[10:11] offset:1024
	global_load_dwordx4 v[76:79], v150, s[10:11] offset:2048
	global_load_dwordx4 v[80:83], v150, s[10:11] offset:3072
	s_add_u32 s10, s10, 0x200000
	s_addc_u32 s11, s11, 0
	global_load_dwordx4 v[84:87], v150, s[10:11]
	global_load_dwordx4 v[88:91], v150, s[10:11] offset:1024
	global_load_dwordx4 v[92:95], v150, s[10:11] offset:2048
	global_load_dwordx4 v[96:99], v150, s[10:11] offset:3072
	s_add_u32 s10, s10, 0x200000
	s_addc_u32 s11, s11, 0
	global_load_dwordx4 v[100:103], v150, s[10:11]
	global_load_dwordx4 v[104:107], v150, s[10:11] offset:1024
	global_load_dwordx4 v[108:111], v150, s[10:11] offset:2048
	global_load_dwordx4 v[112:115], v150, s[10:11] offset:3072
	s_add_u32 s10, s10, 0x200000
	s_addc_u32 s11, s11, 0
	global_load_dwordx4 v[166:169], v150, s[10:11]
	global_load_dwordx4 v[170:173], v150, s[10:11] offset:1024
	global_load_dwordx4 v[174:177], v150, s[10:11] offset:2048
	global_load_dwordx4 v[178:181], v150, s[10:11] offset:3072
	s_add_u32 s10, s10, 0x200000
	s_addc_u32 s11, s11, 0
	global_load_dwordx4 v[182:185], v150, s[10:11]
	global_load_dwordx4 v[186:189], v150, s[10:11] offset:1024
	global_load_dwordx4 v[190:193], v150, s[10:11] offset:2048
	global_load_dwordx4 v[194:197], v150, s[10:11] offset:3072
	s_waitcnt vmcnt(0)
; __device__ __forceinline__ void xcd_barrier(const XcdBarrier& b) {
;     asm volatile("s_waitcnt vmcnt(0)" ::: "memory");
;     __syncthreads();
;     if (threadIdx.x == 0) {
;         unsigned* bar = b.bar;
;         __builtin_amdgcn_s_waitcnt(0);
;         unsigned nloc = b.st[0], nx = b.st[1];
;         if (nloc == 0u) { xcd_barrier_complete(bar, b.x, nloc, nx); b.st[0] = nloc; b.st[1] = nx; }
; __device__ __forceinline__ void res_fix_phase(const Params& p) {
;   u16* xb = (u16*)(p.ws + O_XB);
;   float* part = (float*)(p.ws + O_PART);
;   const int lane = threadIdx.x & 63, wave = threadIdx.x >> 6;
;   for (int row = NP + blockIdx.x * 8 + wave; row < MT; row += gridDim.x * 8) {
;     const float* xr = p.out + (size_t)row * 1024;
;     float ss = 0.f;
; #pragma unroll
;     for (int i = 0; i < 4; i++) {
;       float4 v = *(const float4*)(xr + i * 256 + lane * 4);
;       ss += v.x * v.x + v.y * v.y + v.z * v.z + v.w * v.w;
;       ushort4 o;
;       o.x = f2bf(v.x); o.y = f2bf(v.y); o.z = f2bf(v.z); o.w = f2bf(v.w);
;       *(ushort4*)(xb + (size_t)row * 1024 + i * 256 + lane * 4) = o;
;     }
;     ss = wsum64(ss);
;     if (lane < 16) part[(size_t)row * 16 + lane] = (lane == 0) ? ss : 0.f;
;   }
; }
	v_pk_add_f32 v[2:3], v[2:3], v[20:21]
	v_pk_add_f32 v[4:5], v[4:5], v[22:23]
	v_pk_add_f32 v[6:7], v[6:7], v[24:25]
	v_pk_add_f32 v[8:9], v[8:9], v[26:27]
	v_pk_add_f32 v[10:11], v[10:11], v[28:29]
	v_pk_add_f32 v[12:13], v[12:13], v[30:31]
	v_pk_add_f32 v[14:15], v[14:15], v[32:33]
	v_pk_add_f32 v[16:17], v[16:17], v[34:35]
	v_pk_add_f32 v[2:3], v[2:3], v[36:37]
	v_pk_add_f32 v[4:5], v[4:5], v[38:39]
	v_pk_add_f32 v[6:7], v[6:7], v[40:41]
	v_pk_add_f32 v[8:9], v[8:9], v[42:43]
	v_pk_add_f32 v[10:11], v[10:11], v[44:45]
	v_pk_add_f32 v[12:13], v[12:13], v[46:47]
	v_pk_add_f32 v[14:15], v[14:15], v[48:49]
	v_pk_add_f32 v[16:17], v[16:17], v[50:51]
	v_pk_add_f32 v[2:3], v[2:3], v[52:53]
	v_pk_add_f32 v[4:5], v[4:5], v[54:55]
	v_pk_add_f32 v[6:7], v[6:7], v[56:57]
	v_pk_add_f32 v[8:9], v[8:9], v[58:59]
	v_pk_add_f32 v[10:11], v[10:11], v[60:61]
	v_pk_add_f32 v[12:13], v[12:13], v[62:63]
	v_pk_add_f32 v[14:15], v[14:15], v[64:65]
	v_pk_add_f32 v[16:17], v[16:17], v[66:67]
	v_pk_add_f32 v[2:3], v[2:3], v[68:69]
	v_pk_add_f32 v[4:5], v[4:5], v[70:71]
	v_pk_add_f32 v[6:7], v[6:7], v[72:73]
	v_pk_add_f32 v[8:9], v[8:9], v[74:75]
	v_pk_add_f32 v[10:11], v[10:11], v[76:77]
	v_pk_add_f32 v[12:13], v[12:13], v[78:79]
	v_pk_add_f32 v[14:15], v[14:15], v[80:81]
	v_pk_add_f32 v[16:17], v[16:17], v[82:83]
	v_pk_add_f32 v[2:3], v[2:3], v[84:85]
	v_pk_add_f32 v[4:5], v[4:5], v[86:87]
	v_pk_add_f32 v[6:7], v[6:7], v[88:89]
	v_pk_add_f32 v[8:9], v[8:9], v[90:91]
	v_pk_add_f32 v[10:11], v[10:11], v[92:93]
	v_pk_add_f32 v[12:13], v[12:13], v[94:95]
	v_pk_add_f32 v[14:15], v[14:15], v[96:97]
	v_pk_add_f32 v[16:17], v[16:17], v[98:99]
	v_pk_add_f32 v[2:3], v[2:3], v[100:101]
	v_pk_add_f32 v[4:5], v[4:5], v[102:103]
	v_pk_add_f32 v[6:7], v[6:7], v[104:105]
	v_pk_add_f32 v[8:9], v[8:9], v[106:107]
	v_pk_add_f32 v[10:11], v[10:11], v[108:109]
	v_pk_add_f32 v[12:13], v[12:13], v[110:111]
	v_pk_add_f32 v[14:15], v[14:15], v[112:113]
	v_pk_add_f32 v[16:17], v[16:17], v[114:115]
	v_pk_add_f32 v[2:3], v[2:3], v[166:167]
	v_pk_add_f32 v[4:5], v[4:5], v[168:169]
	v_pk_add_f32 v[6:7], v[6:7], v[170:171]
	v_pk_add_f32 v[8:9], v[8:9], v[172:173]
	v_pk_add_f32 v[10:11], v[10:11], v[174:175]
	v_pk_add_f32 v[12:13], v[12:13], v[176:177]
	v_pk_add_f32 v[14:15], v[14:15], v[178:179]
	v_pk_add_f32 v[16:17], v[16:17], v[180:181]
	v_pk_add_f32 v[2:3], v[2:3], v[182:183]
	v_pk_add_f32 v[4:5], v[4:5], v[184:185]
	v_pk_add_f32 v[6:7], v[6:7], v[186:187]
	v_pk_add_f32 v[8:9], v[8:9], v[188:189]
	v_pk_add_f32 v[10:11], v[10:11], v[190:191]
	v_pk_add_f32 v[12:13], v[12:13], v[192:193]
	v_pk_add_f32 v[14:15], v[14:15], v[194:195]
	v_pk_add_f32 v[16:17], v[16:17], v[196:197]
	global_store_dwordx4 v150, v[2:5], s[8:9]
	global_store_dwordx4 v150, v[6:9], s[8:9] offset:1024
	global_store_dwordx4 v150, v[10:13], s[8:9] offset:2048
	global_store_dwordx4 v150, v[14:17], s[8:9] offset:3072
	v_mul_f32_e32 v154, v2, v2
	v_fmac_f32_e32 v154, v3, v3
	v_fmac_f32_e32 v154, v4, v4
	v_fmac_f32_e32 v154, v5, v5
	v_fmac_f32_e32 v154, v6, v6
	v_fmac_f32_e32 v154, v7, v7
	v_fmac_f32_e32 v154, v8, v8
	v_fmac_f32_e32 v154, v9, v9
	v_fmac_f32_e32 v154, v10, v10
	v_fmac_f32_e32 v154, v11, v11
	v_fmac_f32_e32 v154, v12, v12
	v_fmac_f32_e32 v154, v13, v13
	v_fmac_f32_e32 v154, v14, v14
	v_fmac_f32_e32 v154, v15, v15
	v_fmac_f32_e32 v154, v16, v16
	v_fmac_f32_e32 v154, v17, v17
	s_add_u32 s3, s2, 16384
	s_lshl_b32 s12, s3, 11
	s_add_u32 s14, s96, 0x2f08100
	s_addc_u32 s15, s97, 0
	s_add_u32 s14, s14, s12
	s_addc_u32 s15, s15, 0
	v_cvt_pk_bf16_f32 v156, v2, v3
	v_cvt_pk_bf16_f32 v157, v4, v5
	v_cvt_pk_bf16_f32 v158, v6, v7
	v_cvt_pk_bf16_f32 v159, v8, v9
	v_cvt_pk_bf16_f32 v160, v10, v11
	v_cvt_pk_bf16_f32 v161, v12, v13
	v_cvt_pk_bf16_f32 v162, v14, v15
	v_cvt_pk_bf16_f32 v163, v16, v17
	global_store_dwordx2 v151, v[156:157], s[14:15]
	global_store_dwordx2 v151, v[158:159], s[14:15] offset:512
	global_store_dwordx2 v151, v[160:161], s[14:15] offset:1024
	global_store_dwordx2 v151, v[162:163], s[14:15] offset:1536
	v_add_f32_dpp v154, v154, v154 quad_perm:[1,0,3,2] row_mask:0xf bank_mask:0xf
	s_nop 1
	v_add_f32_dpp v154, v154, v154 quad_perm:[2,3,0,1] row_mask:0xf bank_mask:0xf
	s_nop 1
	v_add_f32_dpp v154, v154, v154 row_half_mirror row_mask:0xf bank_mask:0xf
	s_nop 1
	v_add_f32_dpp v154, v154, v154 row_mirror row_mask:0xf bank_mask:0xf
	v_mov_b32_e32 v155, v154
	s_nop 1
	v_permlane16_swap_b32_e32 v155, v154
	v_add_f32_e32 v154, v154, v155
	v_mov_b32_e32 v155, v154
	s_nop 1
	v_permlane32_swap_b32_e32 v155, v154
	v_add_f32_e32 v154, v154, v155
	v_cndmask_b32_e64 v155, 0, v154, s[20:21]
	s_lshl_b32 s12, s3, 6
	s_add_u32 s14, s96, 0x2e00100
	s_addc_u32 s15, s97, 0
	s_add_u32 s14, s14, s12
	s_addc_u32 s15, s15, 0
	s_mov_b64 s[16:17], exec
	s_mov_b64 exec, s[22:23]
	s_nop 1
	global_store_dword v152, v155, s[14:15]
	s_mov_b64 exec, s[16:17]
.Lrf_done_12:
.LBB0_1515:
	s_cmp_lt_i32 s40, 14
	s_cselect_b64 s[4:5], -1, 0
	s_cmp_gt_i32 s40, 13
	s_cselect_b64 s[0:1], -1, 0
	s_cmp_lt_i32 s41, 13
	s_cselect_b64 s[2:3], -1, 0
	s_or_b64 s[0:1], s[0:1], s[2:3]
	s_and_b64 vcc, exec, s[0:1]
	s_cbranch_vccnz .LBB0_1576
	s_andn2_b64 vcc, exec, s[6:7]
	s_cbranch_vccnz .LBB0_1566
	s_waitcnt vmcnt(0)
	s_waitcnt lgkmcnt(0)
	s_barrier
	s_and_saveexec_b64 s[0:1], s[68:69]
	s_cbranch_execz .LBB0_1565
	v_mov_b32_e32 v0, 0x1c040
	s_waitcnt vmcnt(0) expcnt(0) lgkmcnt(0)
	ds_read_b32 v2, v0
	v_mov_b32_e32 v0, 0x1c044
	ds_read_b32 v0, v0
	s_waitcnt lgkmcnt(1)
	v_cmp_ne_u32_e32 vcc, 0, v2
	s_cbranch_vccnz .LBB0_1533
	v_readlane_b32 s2, v254, 17
	s_mul_i32 s33, s43, s2
	s_add_u32 s2, s96, 0xf928300
	s_addc_u32 s3, s97, 0
	s_add_u32 s6, s96, 0xf928500
	s_addc_u32 s7, s97, 0
	s_add_u32 s8, s96, 0xf928600
	s_addc_u32 s9, s97, 0
	s_add_u32 s10, s96, 0xf928700
	s_addc_u32 s11, s97, 0
	s_add_u32 s12, s96, 0xf928800
	s_addc_u32 s13, s97, 0
	s_add_u32 s14, s96, 0xf928900
	s_addc_u32 s15, s97, 0
	s_add_u32 s16, s96, 0xf928a00
	s_addc_u32 s17, s97, 0
	s_add_u32 s18, s96, 0xf928b00
	s_addc_u32 s19, s97, 0
	s_add_u32 s20, s96, 0xf928c00
	s_addc_u32 s21, s97, 0
	s_add_u32 s22, s96, 0xf928d00
	s_addc_u32 s23, s97, 0
	s_add_u32 s24, s96, 0xf928e00
	s_addc_u32 s25, s97, 0
	s_add_u32 s26, s96, 0xf928f00
	s_addc_u32 s27, s97, 0
	s_add_u32 s28, s96, 0xf929000
	s_addc_u32 s29, s97, 0
	s_add_u32 s30, s96, 0xf929100
	s_addc_u32 s31, s97, 0
	s_add_u32 s34, s96, 0xf929200
	s_addc_u32 s35, s97, 0
	s_add_u32 s36, s96, 0xf929300
	s_addc_u32 s37, s97, 0
	s_add_u32 s38, s96, 0xf929400
	s_mul_i32 s33, s33, s42
	s_addc_u32 s39, s97, 0
	s_mov_b32 s50, 1
	v_mov_b32_e32 v16, 0
	s_branch .LBB0_1521

; __device__ __forceinline__ void xcd_barrier(const XcdBarrier& b) {
;     asm volatile("s_waitcnt vmcnt(0)" ::: "memory");
;     __syncthreads();
;     if (threadIdx.x == 0) {
;         unsigned* bar = b.bar;
;         __builtin_amdgcn_s_waitcnt(0);
;         unsigned nloc = b.st[0], nx = b.st[1];
;         if (nloc == 0u) { xcd_barrier_complete(bar, b.x, nloc, nx); b.st[0] = nloc; b.st[1] = nx; }
; __device__ __forceinline__ void res_fix_phase(const Params& p) {
;   u16* xb = (u16*)(p.ws + O_XB);
;   float* part = (float*)(p.ws + O_PART);
;   const int lane = threadIdx.x & 63, wave = threadIdx.x >> 6;
;   for (int row = NP + blockIdx.x * 8 + wave; row < MT; row += gridDim.x * 8) {
;     const float* xr = p.out + (size_t)row * 1024;
;     float ss = 0.f;
; #pragma unroll
;     for (int i = 0; i < 4; i++) {
;       float4 v = *(const float4*)(xr + i * 256 + lane * 4);
;       ss += v.x * v.x + v.y * v.y + v.z * v.z + v.w * v.w;
;       ushort4 o;
;       o.x = f2bf(v.x); o.y = f2bf(v.y); o.z = f2bf(v.z); o.w = f2bf(v.w);
;       *(ushort4*)(xb + (size_t)row * 1024 + i * 256 + lane * 4) = o;
;     }
;     ss = wsum64(ss);
;     if (lane < 16) part[(size_t)row * 16 + lane] = (lane == 0) ? ss : 0.f;
;   }
; }
.Lrf_done_17:
.LBB0_2019:
	s_cmp_lt_i32 s40, 19
	s_cselect_b64 s[4:5], -1, 0
	s_cmp_gt_i32 s40, 18
	s_cselect_b64 s[0:1], -1, 0
	s_cmp_lt_i32 s41, 18
	s_cselect_b64 s[2:3], -1, 0
	s_or_b64 s[0:1], s[0:1], s[2:3]
	s_and_b64 vcc, exec, s[0:1]
	s_cbranch_vccnz .LBB0_2080
	s_andn2_b64 vcc, exec, s[6:7]
	s_cbranch_vccnz .LBB0_2070
	s_waitcnt vmcnt(0)
	s_waitcnt lgkmcnt(0)
	s_barrier
	s_and_saveexec_b64 s[0:1], s[68:69]
	s_cbranch_execz .LBB0_2069
	v_mov_b32_e32 v0, 0x1c040
	s_waitcnt vmcnt(0) expcnt(0) lgkmcnt(0)
	ds_read_b32 v2, v0
	v_mov_b32_e32 v0, 0x1c044
	ds_read_b32 v0, v0
	s_waitcnt lgkmcnt(1)
	v_cmp_ne_u32_e32 vcc, 0, v2
	s_cbranch_vccnz .LBB0_2037
	v_readlane_b32 s2, v254, 17
	s_mul_i32 s33, s43, s2
	s_add_u32 s2, s96, 0xf928300
	s_addc_u32 s3, s97, 0
	s_add_u32 s6, s96, 0xf928500
	s_addc_u32 s7, s97, 0
	s_add_u32 s8, s96, 0xf928600
	s_addc_u32 s9, s97, 0
	s_add_u32 s10, s96, 0xf928700
	s_addc_u32 s11, s97, 0
	s_add_u32 s12, s96, 0xf928800
	s_addc_u32 s13, s97, 0
	s_add_u32 s14, s96, 0xf928900
	s_addc_u32 s15, s97, 0
	s_add_u32 s16, s96, 0xf928a00
	s_addc_u32 s17, s97, 0
	s_add_u32 s18, s96, 0xf928b00
	s_addc_u32 s19, s97, 0
	s_add_u32 s20, s96, 0xf928c00
	s_addc_u32 s21, s97, 0
	s_add_u32 s22, s96, 0xf928d00
	s_addc_u32 s23, s97, 0
	s_add_u32 s24, s96, 0xf928e00
	s_addc_u32 s25, s97, 0
	s_add_u32 s26, s96, 0xf928f00
	s_addc_u32 s27, s97, 0
	s_add_u32 s28, s96, 0xf929000
	s_addc_u32 s29, s97, 0
	s_add_u32 s30, s96, 0xf929100
	s_addc_u32 s31, s97, 0
	s_add_u32 s34, s96, 0xf929200
	s_addc_u32 s35, s97, 0
	s_add_u32 s36, s96, 0xf929300
	s_addc_u32 s37, s97, 0
	s_add_u32 s38, s96, 0xf929400
	s_mul_i32 s33, s33, s42
	s_addc_u32 s39, s97, 0
	s_mov_b32 s50, 1
	v_mov_b32_e32 v16, 0
	s_branch .LBB0_2025

; __device__ __forceinline__ void final_phase(const Params& p) {
;   const float* part = (const float*)(p.ws + O_PART);
;   const float* g = p.in[40];
;   const int lane = threadIdx.x & 63, wave = threadIdx.x >> 6;
;   for (int row = blockIdx.x * 8 + wave; row < MT; row += gridDim.x * 8) {
;     float s = (lane < 16) ? part[(size_t)row * 16 + lane] : 0.f;
;     s = wsum64(s);
;     const float rs = rsqrtf(s * (1.0f / 1024.0f) + 1e-6f);
;     float* xr = p.out + (size_t)row * 1024;
; #pragma unroll
;     for (int i = 0; i < 4; i++) {
;       float4 v = *(float4*)(xr + i * 256 + lane * 4);
;       float4 gg = *(const float4*)(g + i * 256 + lane * 4);
;       v.x *= rs * gg.x; v.y *= rs * gg.y; v.z *= rs * gg.z; v.w *= rs * gg.w;
;       *(float4*)(xr + i * 256 + lane * 4) = v;
;     }
;   }
.LBB0_2340:
	v_lshrrev_b32_e32 v42, 6, v128
	v_and_b32_e32 v43, 63, v128
	v_readlane_b32 s1, v254, 0
	v_readfirstlane_b32 s0, v42
	v_lshlrev_b32_e32 v40, 4, v43
	v_and_b32_e32 v44, 15, v43
	v_lshlrev_b32_e32 v41, 2, v44
	v_cmp_gt_u32_e32 vcc, 16, v43
	s_lshl_b32 s1, s1, 3
	s_add_u32 s2, s1, s0
	s_lshl_b32 s12, s42, 3
	s_add_u32 s16, s96, 0x9408100
	s_addc_u32 s17, s97, 0
	s_add_u32 s96, s96, 0x2e00100
	s_addc_u32 s97, s97, 0
	global_load_dwordx4 v[16:19], v40, s[92:93]
	global_load_dwordx4 v[20:23], v40, s[92:93] offset:1024
	global_load_dwordx4 v[24:27], v40, s[92:93] offset:2048
	global_load_dwordx4 v[28:31], v40, s[92:93] offset:3072
	s_mov_b32 s14, s2
	s_lshl_b32 s4, s2, 12
	s_add_u32 s8, s94, s4
	s_addc_u32 s9, s95, 0
	s_lshl_b32 s4, s2, 6
	s_add_u32 s6, s96, s4
	s_addc_u32 s7, s97, 0
	global_load_dwordx4 v[0:3], v40, s[8:9]
	global_load_dwordx4 v[4:7], v40, s[8:9] offset:1024
	global_load_dwordx4 v[8:11], v40, s[8:9] offset:2048
	global_load_dwordx4 v[12:15], v40, s[8:9] offset:3072
	global_load_dword v32, v41, s[6:7]
	s_add_u32 s2, s2, s12
	s_mov_b32 s15, s2
	s_lshl_b32 s4, s2, 12
	s_add_u32 s10, s94, s4
	s_addc_u32 s11, s95, 0
	s_lshl_b32 s4, s2, 6
	s_add_u32 s6, s96, s4
	s_addc_u32 s7, s97, 0
	global_load_dwordx4 v[48:51], v40, s[10:11]
	global_load_dwordx4 v[52:55], v40, s[10:11] offset:1024
	global_load_dwordx4 v[56:59], v40, s[10:11] offset:2048
	global_load_dwordx4 v[60:63], v40, s[10:11] offset:3072
	global_load_dword v80, v41, s[6:7]
	s_waitcnt vmcnt(5)
	s_cmp_lt_u32 s14, 16384
	s_cbranch_scc1 .Lfin_prompt_f
	s_lshl_b32 s4, s14, 12
	s_add_u32 s6, s16, s4
	s_addc_u32 s7, s17, 0
	global_load_dwordx4 v[96:99], v40, s[6:7]
	global_load_dwordx4 v[100:103], v40, s[6:7] offset:1024
	global_load_dwordx4 v[104:107], v40, s[6:7] offset:2048
	global_load_dwordx4 v[108:111], v40, s[6:7] offset:3072
	s_add_u32 s6, s6, 0x200000
	s_addc_u32 s7, s7, 0
	global_load_dwordx4 v[112:115], v40, s[6:7]
	global_load_dwordx4 v[116:119], v40, s[6:7] offset:1024
	global_load_dwordx4 v[120:123], v40, s[6:7] offset:2048
	global_load_dwordx4 v[124:127], v40, s[6:7] offset:3072
	s_add_u32 s6, s6, 0x200000
	s_addc_u32 s7, s7, 0
	global_load_dwordx4 v[128:131], v40, s[6:7]
	global_load_dwordx4 v[132:135], v40, s[6:7] offset:1024
	global_load_dwordx4 v[136:139], v40, s[6:7] offset:2048
	global_load_dwordx4 v[140:143], v40, s[6:7] offset:3072
	s_add_u32 s6, s6, 0x200000
	s_addc_u32 s7, s7, 0
	global_load_dwordx4 v[144:147], v40, s[6:7]
	global_load_dwordx4 v[148:151], v40, s[6:7] offset:1024
	global_load_dwordx4 v[152:155], v40, s[6:7] offset:2048
	global_load_dwordx4 v[156:159], v40, s[6:7] offset:3072
	s_add_u32 s6, s6, 0x200000
	s_addc_u32 s7, s7, 0
	global_load_dwordx4 v[160:163], v40, s[6:7]
	global_load_dwordx4 v[164:167], v40, s[6:7] offset:1024
	global_load_dwordx4 v[168:171], v40, s[6:7] offset:2048
	global_load_dwordx4 v[172:175], v40, s[6:7] offset:3072
	s_add_u32 s6, s6, 0x200000
	s_addc_u32 s7, s7, 0
	global_load_dwordx4 v[176:179], v40, s[6:7]
	global_load_dwordx4 v[180:183], v40, s[6:7] offset:1024
	global_load_dwordx4 v[184:187], v40, s[6:7] offset:2048
	global_load_dwordx4 v[188:191], v40, s[6:7] offset:3072
	s_add_u32 s6, s6, 0x200000
	s_addc_u32 s7, s7, 0
	global_load_dwordx4 v[192:195], v40, s[6:7]
	global_load_dwordx4 v[196:199], v40, s[6:7] offset:1024
	global_load_dwordx4 v[200:203], v40, s[6:7] offset:2048
	global_load_dwordx4 v[204:207], v40, s[6:7] offset:3072
	s_add_u32 s6, s6, 0x200000
	s_addc_u32 s7, s7, 0
	global_load_dwordx4 v[208:211], v40, s[6:7]
	global_load_dwordx4 v[212:215], v40, s[6:7] offset:1024
	global_load_dwordx4 v[216:219], v40, s[6:7] offset:2048
	global_load_dwordx4 v[220:223], v40, s[6:7] offset:3072
	s_waitcnt vmcnt(0)
	v_pk_add_f32 v[0:1], v[0:1], v[96:97]
	v_pk_add_f32 v[2:3], v[2:3], v[98:99]
	v_pk_add_f32 v[4:5], v[4:5], v[100:101]
	v_pk_add_f32 v[6:7], v[6:7], v[102:103]
	v_pk_add_f32 v[8:9], v[8:9], v[104:105]
	v_pk_add_f32 v[10:11], v[10:11], v[106:107]
	v_pk_add_f32 v[12:13], v[12:13], v[108:109]
	v_pk_add_f32 v[14:15], v[14:15], v[110:111]
	v_pk_add_f32 v[0:1], v[0:1], v[112:113]
	v_pk_add_f32 v[2:3], v[2:3], v[114:115]
	v_pk_add_f32 v[4:5], v[4:5], v[116:117]
	v_pk_add_f32 v[6:7], v[6:7], v[118:119]
	v_pk_add_f32 v[8:9], v[8:9], v[120:121]
	v_pk_add_f32 v[10:11], v[10:11], v[122:123]
	v_pk_add_f32 v[12:13], v[12:13], v[124:125]
	v_pk_add_f32 v[14:15], v[14:15], v[126:127]
	v_pk_add_f32 v[0:1], v[0:1], v[128:129]
	v_pk_add_f32 v[2:3], v[2:3], v[130:131]
	v_pk_add_f32 v[4:5], v[4:5], v[132:133]
	v_pk_add_f32 v[6:7], v[6:7], v[134:135]
	v_pk_add_f32 v[8:9], v[8:9], v[136:137]
	v_pk_add_f32 v[10:11], v[10:11], v[138:139]
	v_pk_add_f32 v[12:13], v[12:13], v[140:141]
	v_pk_add_f32 v[14:15], v[14:15], v[142:143]
	v_pk_add_f32 v[0:1], v[0:1], v[144:145]
	v_pk_add_f32 v[2:3], v[2:3], v[146:147]
	v_pk_add_f32 v[4:5], v[4:5], v[148:149]
	v_pk_add_f32 v[6:7], v[6:7], v[150:151]
	v_pk_add_f32 v[8:9], v[8:9], v[152:153]
	v_pk_add_f32 v[10:11], v[10:11], v[154:155]
	v_pk_add_f32 v[12:13], v[12:13], v[156:157]
	v_pk_add_f32 v[14:15], v[14:15], v[158:159]
	v_pk_add_f32 v[0:1], v[0:1], v[160:161]
	v_pk_add_f32 v[2:3], v[2:3], v[162:163]
	v_pk_add_f32 v[4:5], v[4:5], v[164:165]
	v_pk_add_f32 v[6:7], v[6:7], v[166:167]
	v_pk_add_f32 v[8:9], v[8:9], v[168:169]
	v_pk_add_f32 v[10:11], v[10:11], v[170:171]
	v_pk_add_f32 v[12:13], v[12:13], v[172:173]
	v_pk_add_f32 v[14:15], v[14:15], v[174:175]
	v_pk_add_f32 v[0:1], v[0:1], v[176:177]
	v_pk_add_f32 v[2:3], v[2:3], v[178:179]
	v_pk_add_f32 v[4:5], v[4:5], v[180:181]
	v_pk_add_f32 v[6:7], v[6:7], v[182:183]
	v_pk_add_f32 v[8:9], v[8:9], v[184:185]
	v_pk_add_f32 v[10:11], v[10:11], v[186:187]
	v_pk_add_f32 v[12:13], v[12:13], v[188:189]
	v_pk_add_f32 v[14:15], v[14:15], v[190:191]
	v_pk_add_f32 v[0:1], v[0:1], v[192:193]
	v_pk_add_f32 v[2:3], v[2:3], v[194:195]
	v_pk_add_f32 v[4:5], v[4:5], v[196:197]
	v_pk_add_f32 v[6:7], v[6:7], v[198:199]
	v_pk_add_f32 v[8:9], v[8:9], v[200:201]
	v_pk_add_f32 v[10:11], v[10:11], v[202:203]
	v_pk_add_f32 v[12:13], v[12:13], v[204:205]
	v_pk_add_f32 v[14:15], v[14:15], v[206:207]
	v_pk_add_f32 v[0:1], v[0:1], v[208:209]
	v_pk_add_f32 v[2:3], v[2:3], v[210:211]
	v_pk_add_f32 v[4:5], v[4:5], v[212:213]
	v_pk_add_f32 v[6:7], v[6:7], v[214:215]
	v_pk_add_f32 v[8:9], v[8:9], v[216:217]
	v_pk_add_f32 v[10:11], v[10:11], v[218:219]
	v_pk_add_f32 v[12:13], v[12:13], v[220:221]
	v_pk_add_f32 v[14:15], v[14:15], v[222:223]
	v_mul_f32_e32 v42, v0, v0
	v_fmac_f32_e32 v42, v1, v1
	v_fmac_f32_e32 v42, v2, v2
	v_fmac_f32_e32 v42, v3, v3
	v_fmac_f32_e32 v42, v4, v4
	v_fmac_f32_e32 v42, v5, v5
	v_fmac_f32_e32 v42, v6, v6
	v_fmac_f32_e32 v42, v7, v7
	v_fmac_f32_e32 v42, v8, v8
	v_fmac_f32_e32 v42, v9, v9
	v_fmac_f32_e32 v42, v10, v10
	v_fmac_f32_e32 v42, v11, v11
	v_fmac_f32_e32 v42, v12, v12
	v_fmac_f32_e32 v42, v13, v13
	v_fmac_f32_e32 v42, v14, v14
	v_fmac_f32_e32 v42, v15, v15
	s_branch .Lfin_sum_f

; __device__ __forceinline__ void final_phase(const Params& p) {
;     ...
;   for (int row = blockIdx.x * 8 + wave; row < MT; row += gridDim.x * 8) {
;     float s = (lane < 16) ? part[(size_t)row * 16 + lane] : 0.f;
;     s = wsum64(s);
;     const float rs = rsqrtf(s * (1.0f / 1024.0f) + 1e-6f);
;     float* xr = p.out + (size_t)row * 1024;
; #pragma unroll
;     for (int i = 0; i < 4; i++) {
;       float4 v = *(float4*)(xr + i * 256 + lane * 4);
;       float4 gg = *(const float4*)(g + i * 256 + lane * 4);
;       v.x *= rs * gg.x; v.y *= rs * gg.y; v.z *= rs * gg.z; v.w *= rs * gg.w;
;       *(float4*)(xr + i * 256 + lane * 4) = v;
;     }
;   }
.Lfin_go_a:
	s_cmp_lt_u32 s15, 16384
	s_cbranch_scc1 .Lfin_prompt_a
	s_lshl_b32 s4, s15, 12
	s_add_u32 s6, s16, s4
	s_addc_u32 s7, s17, 0
	global_load_dwordx4 v[96:99], v40, s[6:7]
	global_load_dwordx4 v[100:103], v40, s[6:7] offset:1024
	global_load_dwordx4 v[104:107], v40, s[6:7] offset:2048
	global_load_dwordx4 v[108:111], v40, s[6:7] offset:3072
	s_add_u32 s6, s6, 0x200000
	s_addc_u32 s7, s7, 0
	global_load_dwordx4 v[112:115], v40, s[6:7]
	global_load_dwordx4 v[116:119], v40, s[6:7] offset:1024
	global_load_dwordx4 v[120:123], v40, s[6:7] offset:2048
	global_load_dwordx4 v[124:127], v40, s[6:7] offset:3072
	s_add_u32 s6, s6, 0x200000
	s_addc_u32 s7, s7, 0
	global_load_dwordx4 v[128:131], v40, s[6:7]
	global_load_dwordx4 v[132:135], v40, s[6:7] offset:1024
	global_load_dwordx4 v[136:139], v40, s[6:7] offset:2048
	global_load_dwordx4 v[140:143], v40, s[6:7] offset:3072
	s_add_u32 s6, s6, 0x200000
	s_addc_u32 s7, s7, 0
	global_load_dwordx4 v[144:147], v40, s[6:7]
	global_load_dwordx4 v[148:151], v40, s[6:7] offset:1024
	global_load_dwordx4 v[152:155], v40, s[6:7] offset:2048
	global_load_dwordx4 v[156:159], v40, s[6:7] offset:3072
	s_add_u32 s6, s6, 0x200000
	s_addc_u32 s7, s7, 0
	global_load_dwordx4 v[160:163], v40, s[6:7]
	global_load_dwordx4 v[164:167], v40, s[6:7] offset:1024
	global_load_dwordx4 v[168:171], v40, s[6:7] offset:2048
	global_load_dwordx4 v[172:175], v40, s[6:7] offset:3072
	s_add_u32 s6, s6, 0x200000
	s_addc_u32 s7, s7, 0
	global_load_dwordx4 v[176:179], v40, s[6:7]
	global_load_dwordx4 v[180:183], v40, s[6:7] offset:1024
	global_load_dwordx4 v[184:187], v40, s[6:7] offset:2048
	global_load_dwordx4 v[188:191], v40, s[6:7] offset:3072
	s_add_u32 s6, s6, 0x200000
	s_addc_u32 s7, s7, 0
	global_load_dwordx4 v[192:195], v40, s[6:7]
	global_load_dwordx4 v[196:199], v40, s[6:7] offset:1024
	global_load_dwordx4 v[200:203], v40, s[6:7] offset:2048
	global_load_dwordx4 v[204:207], v40, s[6:7] offset:3072
	s_add_u32 s6, s6, 0x200000
	s_addc_u32 s7, s7, 0
	global_load_dwordx4 v[208:211], v40, s[6:7]
	global_load_dwordx4 v[212:215], v40, s[6:7] offset:1024
	global_load_dwordx4 v[216:219], v40, s[6:7] offset:2048
	global_load_dwordx4 v[220:223], v40, s[6:7] offset:3072
	s_waitcnt vmcnt(0)
	v_pk_add_f32 v[48:49], v[48:49], v[96:97]
	v_pk_add_f32 v[50:51], v[50:51], v[98:99]
	v_pk_add_f32 v[52:53], v[52:53], v[100:101]
	v_pk_add_f32 v[54:55], v[54:55], v[102:103]
	v_pk_add_f32 v[56:57], v[56:57], v[104:105]
	v_pk_add_f32 v[58:59], v[58:59], v[106:107]
	v_pk_add_f32 v[60:61], v[60:61], v[108:109]
	v_pk_add_f32 v[62:63], v[62:63], v[110:111]
	v_pk_add_f32 v[48:49], v[48:49], v[112:113]
	v_pk_add_f32 v[50:51], v[50:51], v[114:115]
	v_pk_add_f32 v[52:53], v[52:53], v[116:117]
	v_pk_add_f32 v[54:55], v[54:55], v[118:119]
	v_pk_add_f32 v[56:57], v[56:57], v[120:121]
	v_pk_add_f32 v[58:59], v[58:59], v[122:123]
	v_pk_add_f32 v[60:61], v[60:61], v[124:125]
	v_pk_add_f32 v[62:63], v[62:63], v[126:127]
	v_pk_add_f32 v[48:49], v[48:49], v[128:129]
	v_pk_add_f32 v[50:51], v[50:51], v[130:131]
	v_pk_add_f32 v[52:53], v[52:53], v[132:133]
	v_pk_add_f32 v[54:55], v[54:55], v[134:135]
	v_pk_add_f32 v[56:57], v[56:57], v[136:137]
	v_pk_add_f32 v[58:59], v[58:59], v[138:139]
	v_pk_add_f32 v[60:61], v[60:61], v[140:141]
	v_pk_add_f32 v[62:63], v[62:63], v[142:143]
	v_pk_add_f32 v[48:49], v[48:49], v[144:145]
	v_pk_add_f32 v[50:51], v[50:51], v[146:147]
	v_pk_add_f32 v[52:53], v[52:53], v[148:149]
	v_pk_add_f32 v[54:55], v[54:55], v[150:151]
	v_pk_add_f32 v[56:57], v[56:57], v[152:153]
	v_pk_add_f32 v[58:59], v[58:59], v[154:155]
	v_pk_add_f32 v[60:61], v[60:61], v[156:157]
	v_pk_add_f32 v[62:63], v[62:63], v[158:159]
	v_pk_add_f32 v[48:49], v[48:49], v[160:161]
	v_pk_add_f32 v[50:51], v[50:51], v[162:163]
	v_pk_add_f32 v[52:53], v[52:53], v[164:165]
	v_pk_add_f32 v[54:55], v[54:55], v[166:167]
	v_pk_add_f32 v[56:57], v[56:57], v[168:169]
	v_pk_add_f32 v[58:59], v[58:59], v[170:171]
	v_pk_add_f32 v[60:61], v[60:61], v[172:173]
	v_pk_add_f32 v[62:63], v[62:63], v[174:175]
	v_pk_add_f32 v[48:49], v[48:49], v[176:177]
	v_pk_add_f32 v[50:51], v[50:51], v[178:179]
	v_pk_add_f32 v[52:53], v[52:53], v[180:181]
	v_pk_add_f32 v[54:55], v[54:55], v[182:183]
	v_pk_add_f32 v[56:57], v[56:57], v[184:185]
	v_pk_add_f32 v[58:59], v[58:59], v[186:187]
	v_pk_add_f32 v[60:61], v[60:61], v[188:189]
	v_pk_add_f32 v[62:63], v[62:63], v[190:191]
	v_pk_add_f32 v[48:49], v[48:49], v[192:193]
	v_pk_add_f32 v[50:51], v[50:51], v[194:195]
	v_pk_add_f32 v[52:53], v[52:53], v[196:197]
	v_pk_add_f32 v[54:55], v[54:55], v[198:199]
	v_pk_add_f32 v[56:57], v[56:57], v[200:201]
	v_pk_add_f32 v[58:59], v[58:59], v[202:203]
	v_pk_add_f32 v[60:61], v[60:61], v[204:205]
	v_pk_add_f32 v[62:63], v[62:63], v[206:207]
	v_pk_add_f32 v[48:49], v[48:49], v[208:209]
	v_pk_add_f32 v[50:51], v[50:51], v[210:211]
	v_pk_add_f32 v[52:53], v[52:53], v[212:213]
	v_pk_add_f32 v[54:55], v[54:55], v[214:215]
	v_pk_add_f32 v[56:57], v[56:57], v[216:217]
	v_pk_add_f32 v[58:59], v[58:59], v[218:219]
	v_pk_add_f32 v[60:61], v[60:61], v[220:221]
	v_pk_add_f32 v[62:63], v[62:63], v[222:223]
	v_mul_f32_e32 v42, v48, v48
	v_fmac_f32_e32 v42, v49, v49
	v_fmac_f32_e32 v42, v50, v50
	v_fmac_f32_e32 v42, v51, v51
	v_fmac_f32_e32 v42, v52, v52
	v_fmac_f32_e32 v42, v53, v53
	v_fmac_f32_e32 v42, v54, v54
	v_fmac_f32_e32 v42, v55, v55
	v_fmac_f32_e32 v42, v56, v56
	v_fmac_f32_e32 v42, v57, v57
	v_fmac_f32_e32 v42, v58, v58
	v_fmac_f32_e32 v42, v59, v59
	v_fmac_f32_e32 v42, v60, v60
	v_fmac_f32_e32 v42, v61, v61
	v_fmac_f32_e32 v42, v62, v62
	v_fmac_f32_e32 v42, v63, v63
	s_branch .Lfin_sum_a

; __device__ __forceinline__ void final_phase(const Params& p) {
;     ...
;   for (int row = blockIdx.x * 8 + wave; row < MT; row += gridDim.x * 8) {
;     float s = (lane < 16) ? part[(size_t)row * 16 + lane] : 0.f;
;     s = wsum64(s);
;     const float rs = rsqrtf(s * (1.0f / 1024.0f) + 1e-6f);
;     float* xr = p.out + (size_t)row * 1024;
; #pragma unroll
;     for (int i = 0; i < 4; i++) {
;       float4 v = *(float4*)(xr + i * 256 + lane * 4);
;       float4 gg = *(const float4*)(g + i * 256 + lane * 4);
;       v.x *= rs * gg.x; v.y *= rs * gg.y; v.z *= rs * gg.z; v.w *= rs * gg.w;
;       *(float4*)(xr + i * 256 + lane * 4) = v;
;     }
;   }
.Lfin_go_b:
	s_cmp_lt_u32 s14, 16384
	s_cbranch_scc1 .Lfin_prompt_b
	s_lshl_b32 s4, s14, 12
	s_add_u32 s6, s16, s4
	s_addc_u32 s7, s17, 0
	global_load_dwordx4 v[96:99], v40, s[6:7]
	global_load_dwordx4 v[100:103], v40, s[6:7] offset:1024
	global_load_dwordx4 v[104:107], v40, s[6:7] offset:2048
	global_load_dwordx4 v[108:111], v40, s[6:7] offset:3072
	s_add_u32 s6, s6, 0x200000
	s_addc_u32 s7, s7, 0
	global_load_dwordx4 v[112:115], v40, s[6:7]
	global_load_dwordx4 v[116:119], v40, s[6:7] offset:1024
	global_load_dwordx4 v[120:123], v40, s[6:7] offset:2048
	global_load_dwordx4 v[124:127], v40, s[6:7] offset:3072
	s_add_u32 s6, s6, 0x200000
	s_addc_u32 s7, s7, 0
	global_load_dwordx4 v[128:131], v40, s[6:7]
	global_load_dwordx4 v[132:135], v40, s[6:7] offset:1024
	global_load_dwordx4 v[136:139], v40, s[6:7] offset:2048
	global_load_dwordx4 v[140:143], v40, s[6:7] offset:3072
	s_add_u32 s6, s6, 0x200000
	s_addc_u32 s7, s7, 0
	global_load_dwordx4 v[144:147], v40, s[6:7]
	global_load_dwordx4 v[148:151], v40, s[6:7] offset:1024
	global_load_dwordx4 v[152:155], v40, s[6:7] offset:2048
	global_load_dwordx4 v[156:159], v40, s[6:7] offset:3072
	s_add_u32 s6, s6, 0x200000
	s_addc_u32 s7, s7, 0
	global_load_dwordx4 v[160:163], v40, s[6:7]
	global_load_dwordx4 v[164:167], v40, s[6:7] offset:1024
	global_load_dwordx4 v[168:171], v40, s[6:7] offset:2048
	global_load_dwordx4 v[172:175], v40, s[6:7] offset:3072
	s_add_u32 s6, s6, 0x200000
	s_addc_u32 s7, s7, 0
	global_load_dwordx4 v[176:179], v40, s[6:7]
	global_load_dwordx4 v[180:183], v40, s[6:7] offset:1024
	global_load_dwordx4 v[184:187], v40, s[6:7] offset:2048
	global_load_dwordx4 v[188:191], v40, s[6:7] offset:3072
	s_add_u32 s6, s6, 0x200000
	s_addc_u32 s7, s7, 0
	global_load_dwordx4 v[192:195], v40, s[6:7]
	global_load_dwordx4 v[196:199], v40, s[6:7] offset:1024
	global_load_dwordx4 v[200:203], v40, s[6:7] offset:2048
	global_load_dwordx4 v[204:207], v40, s[6:7] offset:3072
	s_add_u32 s6, s6, 0x200000
	s_addc_u32 s7, s7, 0
	global_load_dwordx4 v[208:211], v40, s[6:7]
	global_load_dwordx4 v[212:215], v40, s[6:7] offset:1024
	global_load_dwordx4 v[216:219], v40, s[6:7] offset:2048
	global_load_dwordx4 v[220:223], v40, s[6:7] offset:3072
	s_waitcnt vmcnt(0)
	v_pk_add_f32 v[0:1], v[0:1], v[96:97]
	v_pk_add_f32 v[2:3], v[2:3], v[98:99]
	v_pk_add_f32 v[4:5], v[4:5], v[100:101]
	v_pk_add_f32 v[6:7], v[6:7], v[102:103]
	v_pk_add_f32 v[8:9], v[8:9], v[104:105]
	v_pk_add_f32 v[10:11], v[10:11], v[106:107]
	v_pk_add_f32 v[12:13], v[12:13], v[108:109]
	v_pk_add_f32 v[14:15], v[14:15], v[110:111]
	v_pk_add_f32 v[0:1], v[0:1], v[112:113]
	v_pk_add_f32 v[2:3], v[2:3], v[114:115]
	v_pk_add_f32 v[4:5], v[4:5], v[116:117]
	v_pk_add_f32 v[6:7], v[6:7], v[118:119]
	v_pk_add_f32 v[8:9], v[8:9], v[120:121]
	v_pk_add_f32 v[10:11], v[10:11], v[122:123]
	v_pk_add_f32 v[12:13], v[12:13], v[124:125]
	v_pk_add_f32 v[14:15], v[14:15], v[126:127]
	v_pk_add_f32 v[0:1], v[0:1], v[128:129]
	v_pk_add_f32 v[2:3], v[2:3], v[130:131]
	v_pk_add_f32 v[4:5], v[4:5], v[132:133]
	v_pk_add_f32 v[6:7], v[6:7], v[134:135]
	v_pk_add_f32 v[8:9], v[8:9], v[136:137]
	v_pk_add_f32 v[10:11], v[10:11], v[138:139]
	v_pk_add_f32 v[12:13], v[12:13], v[140:141]
	v_pk_add_f32 v[14:15], v[14:15], v[142:143]
	v_pk_add_f32 v[0:1], v[0:1], v[144:145]
	v_pk_add_f32 v[2:3], v[2:3], v[146:147]
	v_pk_add_f32 v[4:5], v[4:5], v[148:149]
	v_pk_add_f32 v[6:7], v[6:7], v[150:151]
	v_pk_add_f32 v[8:9], v[8:9], v[152:153]
	v_pk_add_f32 v[10:11], v[10:11], v[154:155]
	v_pk_add_f32 v[12:13], v[12:13], v[156:157]
	v_pk_add_f32 v[14:15], v[14:15], v[158:159]
	v_pk_add_f32 v[0:1], v[0:1], v[160:161]
	v_pk_add_f32 v[2:3], v[2:3], v[162:163]
	v_pk_add_f32 v[4:5], v[4:5], v[164:165]
	v_pk_add_f32 v[6:7], v[6:7], v[166:167]
	v_pk_add_f32 v[8:9], v[8:9], v[168:169]
	v_pk_add_f32 v[10:11], v[10:11], v[170:171]
	v_pk_add_f32 v[12:13], v[12:13], v[172:173]
	v_pk_add_f32 v[14:15], v[14:15], v[174:175]
	v_pk_add_f32 v[0:1], v[0:1], v[176:177]
	v_pk_add_f32 v[2:3], v[2:3], v[178:179]
	v_pk_add_f32 v[4:5], v[4:5], v[180:181]
	v_pk_add_f32 v[6:7], v[6:7], v[182:183]
	v_pk_add_f32 v[8:9], v[8:9], v[184:185]
	v_pk_add_f32 v[10:11], v[10:11], v[186:187]
	v_pk_add_f32 v[12:13], v[12:13], v[188:189]
	v_pk_add_f32 v[14:15], v[14:15], v[190:191]
	v_pk_add_f32 v[0:1], v[0:1], v[192:193]
	v_pk_add_f32 v[2:3], v[2:3], v[194:195]
	v_pk_add_f32 v[4:5], v[4:5], v[196:197]
	v_pk_add_f32 v[6:7], v[6:7], v[198:199]
	v_pk_add_f32 v[8:9], v[8:9], v[200:201]
	v_pk_add_f32 v[10:11], v[10:11], v[202:203]
	v_pk_add_f32 v[12:13], v[12:13], v[204:205]
	v_pk_add_f32 v[14:15], v[14:15], v[206:207]
	v_pk_add_f32 v[0:1], v[0:1], v[208:209]
	v_pk_add_f32 v[2:3], v[2:3], v[210:211]
	v_pk_add_f32 v[4:5], v[4:5], v[212:213]
	v_pk_add_f32 v[6:7], v[6:7], v[214:215]
	v_pk_add_f32 v[8:9], v[8:9], v[216:217]
	v_pk_add_f32 v[10:11], v[10:11], v[218:219]
	v_pk_add_f32 v[12:13], v[12:13], v[220:221]
	v_pk_add_f32 v[14:15], v[14:15], v[222:223]
	v_mul_f32_e32 v42, v0, v0
	v_fmac_f32_e32 v42, v1, v1
	v_fmac_f32_e32 v42, v2, v2
	v_fmac_f32_e32 v42, v3, v3
	v_fmac_f32_e32 v42, v4, v4
	v_fmac_f32_e32 v42, v5, v5
	v_fmac_f32_e32 v42, v6, v6
	v_fmac_f32_e32 v42, v7, v7
	v_fmac_f32_e32 v42, v8, v8
	v_fmac_f32_e32 v42, v9, v9
	v_fmac_f32_e32 v42, v10, v10
	v_fmac_f32_e32 v42, v11, v11
	v_fmac_f32_e32 v42, v12, v12
	v_fmac_f32_e32 v42, v13, v13
	v_fmac_f32_e32 v42, v14, v14
	v_fmac_f32_e32 v42, v15, v15
	s_branch .Lfin_sum_b
